# attention: MFMA-first tile head - first K fragments resident at the barrier (read before it), DMA issue block behind the second QK MFMA
# speedup vs baseline: 1.0081x; 1.0054x over previous
.Latt_diff_p0:
.LBB0_107:
.LBB0_116:
	v_mfma_f32_32x32x16_bf16 v[64:79], v[112:115], v[130:133], v[96:111]
	ds_read_b128 v[112:115], v242 offset:4608
	v_mfma_f32_32x32x16_bf16 v[64:79], v[116:119], v[134:137], v[64:79]
	ds_read_b128 v[116:119], v242 offset:4640
	s_add_i32 s30, s52, 2
	s_cmp_ge_u32 s30, s21
	s_cselect_b64 s[46:47], -1, 0
	s_cbranch_scc1 .Latt_diff_dmaend
	s_cmp_lt_u32 s52, 2
	s_cselect_b32 s48, s45, s43
	s_mul_i32 s55, s50, 0x2400
	s_add_i32 s56, s55, s41
	s_mov_b32 m0, s56
	v_lshl_add_u32 v244, s48, 12, v153
	global_load_lds_dwordx4 v244, s[18:19]
	s_ashr_i32 s49, s48, 31
	s_lshl_b64 s[30:31], s[48:49], 1
	s_add_i32 s55, s55, s56
	s_add_i32 m0, s55, 0x6c00
	s_add_u32 s30, s39, s30
	s_addc_u32 s31, s42, s31
	global_load_lds_dwordx4 v150, s[30:31]
	s_add_i32 m0, s55, 0x8c00
	s_and_b64 vcc, exec, s[14:15]
	global_load_lds_dwordx4 v148, s[30:31]
	s_cbranch_vccz .Latt_diff_dmax
.Latt_diff_dmaend:
	v_mfma_f32_32x32x16_bf16 v[64:79], v[120:123], v[138:141], v[64:79]
	ds_read_b128 v[120:123], v242 offset:4672
	v_mfma_f32_32x32x16_bf16 v[64:79], v[124:127], v[142:145], v[64:79]
	ds_read_b128 v[124:127], v242 offset:4704
	s_waitcnt lgkmcnt(2)
	v_mfma_f32_32x32x16_bf16 v[80:95], v[112:115], v[130:133], v[96:111]
	v_mfma_f32_32x32x16_bf16 v[80:95], v[116:119], v[134:137], v[80:95]
	s_waitcnt lgkmcnt(0)
	v_mfma_f32_32x32x16_bf16 v[80:95], v[120:123], v[138:141], v[80:95]
	v_mfma_f32_32x32x16_bf16 v[80:95], v[124:127], v[142:145], v[80:95]
	ds_read_b128 v[112:115], v243 offset:27648
	ds_read_b128 v[116:119], v243 offset:32256
	ds_read_b128 v[120:123], v243 offset:36864
	ds_read_b128 v[124:127], v243 offset:41472
	s_cmp_eq_u32 s52, 0
	s_cselect_b32 s31, 0xff7fffff, 0
	v_max3_f32 v227, v64, v65, v66
	v_max3_f32 v228, v67, v68, v69
	v_max3_f32 v227, v227, v70, v71
	v_max3_f32 v228, v228, v72, v73
	v_max3_f32 v227, v227, v74, v75
	v_max3_f32 v228, v228, v76, v77
	v_max3_f32 v227, v227, v78, v79
	v_max3_f32 v229, v80, v81, v82
	v_max3_f32 v226, v83, v84, v85
	v_max3_f32 v229, v229, v86, v87
	v_max3_f32 v226, v226, v88, v89
	v_max3_f32 v229, v229, v90, v91
	v_max3_f32 v226, v226, v92, v93
	v_max3_f32 v229, v229, v94, v95
	v_max3_f32 v226, v226, v227, v228
	v_max_f32_e32 v226, v226, v229
	v_cmp_lt_f32_e32 vcc, s58, v226
	s_cmp_eq_u32 s52, 0
	s_cbranch_scc1 .Latt_diff_rare
	s_cbranch_vccnz .Latt_diff_rare

.Latt_mla_p0:
.LBB0_178:
.LBB0_191:
	v_mfma_f32_32x32x16_bf16 v[64:79], v[112:115], v[130:133], v[96:111]
	ds_read_b128 v[112:115], v217 offset:160
	v_mfma_f32_32x32x16_bf16 v[64:79], v[116:119], v[134:137], v[64:79]
	ds_read_b128 v[116:119], v217 offset:192
	s_add_i32 s30, s55, 2
	s_cmp_ge_u32 s30, s20
	s_cselect_b64 s[60:61], -1, 0
	s_cbranch_scc1 .Latt_mla_dmaend
	s_cmp_lt_u32 s55, 2
	s_cselect_b32 s62, s51, s49
	s_mul_i32 s57, s52, 0x6400
	s_add_i32 s57, s57, s42
	s_mov_b32 m0, s57
	v_mad_u32_u24 v211, s62, v237, v222
	global_load_lds_dwordx4 v211, s[2:3]
	s_add_i32 m0, s57, 0x2000
	v_mad_u32_u24 v211, s62, v239, v224
	global_load_lds_dwordx4 v211, s[2:3]
	s_add_i32 m0, s57, 0x4000
	v_mad_u32_u24 v211, s62, v241, v226
	global_load_lds_dwordx4 v211, s[2:3]
	s_ashr_i32 s63, s62, 31
	s_lshl_b64 s[30:31], s[62:63], 1
	s_mul_i32 s63, s52, 0x4800
	s_add_i32 s63, s63, s42
	s_add_i32 m0, s63, 0x12c00
	s_add_u32 s30, s21, s30
	s_addc_u32 s31, s43, s31
	global_load_lds_dwordx4 v202, s[30:31]
	s_add_i32 m0, s63, 0x14c00
	s_and_b64 vcc, exec, s[18:19]
	global_load_lds_dwordx4 v200, s[30:31]
	s_cbranch_vccz .Latt_mla_dmax
.Latt_mla_dmaend:
	v_mfma_f32_32x32x16_bf16 v[64:79], v[120:123], v[138:141], v[64:79]
	ds_read_b128 v[120:123], v217 offset:224
	v_mfma_f32_32x32x16_bf16 v[64:79], v[124:127], v[142:145], v[64:79]
	ds_read_b128 v[124:127], v217 offset:256
	v_mfma_f32_32x32x16_bf16 v[64:79], v[250:253], v[146:149], v[64:79]
	ds_read_b128 v[250:253], v217 offset:288
	s_waitcnt lgkmcnt(3)
	v_mfma_f32_32x32x16_bf16 v[64:79], v[112:115], v[150:153], v[64:79]
	ds_read_b128 v[112:115], v217 offset:320
	v_mfma_f32_32x32x16_bf16 v[64:79], v[116:119], v[154:157], v[64:79]
	ds_read_b128 v[116:119], v217 offset:352
	s_waitcnt lgkmcnt(3)
	v_mfma_f32_32x32x16_bf16 v[64:79], v[120:123], v[158:161], v[64:79]
	ds_read_b128 v[120:123], v217 offset:12800
	v_mfma_f32_32x32x16_bf16 v[64:79], v[124:127], v[162:165], v[64:79]
	ds_read_b128 v[124:127], v217 offset:12832
	s_waitcnt lgkmcnt(3)
	v_mfma_f32_32x32x16_bf16 v[64:79], v[250:253], v[166:169], v[64:79]
	ds_read_b128 v[250:253], v217 offset:12864
	v_mfma_f32_32x32x16_bf16 v[64:79], v[112:115], v[170:173], v[64:79]
	ds_read_b128 v[112:115], v217 offset:12896
	s_waitcnt lgkmcnt(3)
	v_mfma_f32_32x32x16_bf16 v[64:79], v[116:119], v[174:177], v[64:79]
	ds_read_b128 v[116:119], v217 offset:12928
	v_mfma_f32_32x32x16_bf16 v[80:95], v[120:123], v[130:133], v[96:111]
	ds_read_b128 v[120:123], v217 offset:12960
	s_waitcnt lgkmcnt(3)
	v_mfma_f32_32x32x16_bf16 v[80:95], v[124:127], v[134:137], v[80:95]
	ds_read_b128 v[124:127], v217 offset:12992
	v_mfma_f32_32x32x16_bf16 v[80:95], v[250:253], v[138:141], v[80:95]
	ds_read_b128 v[250:253], v217 offset:13024
	s_waitcnt lgkmcnt(3)
	v_mfma_f32_32x32x16_bf16 v[80:95], v[112:115], v[142:145], v[80:95]
	ds_read_b128 v[112:115], v217 offset:13056
	v_mfma_f32_32x32x16_bf16 v[80:95], v[116:119], v[146:149], v[80:95]
	ds_read_b128 v[116:119], v217 offset:13088
	v_max3_f32 v211, v64, v65, v66
	s_waitcnt lgkmcnt(3)
	v_mfma_f32_32x32x16_bf16 v[80:95], v[120:123], v[150:153], v[80:95]
	ds_read_b128 v[120:123], v217 offset:13120
	v_max3_f32 v213, v67, v68, v69
	v_mfma_f32_32x32x16_bf16 v[80:95], v[124:127], v[154:157], v[80:95]
	ds_read_b128 v[124:127], v217 offset:13152
	v_max3_f32 v211, v211, v70, v71
	s_waitcnt lgkmcnt(3)
	v_mfma_f32_32x32x16_bf16 v[80:95], v[250:253], v[158:161], v[80:95]
	v_max3_f32 v213, v213, v72, v73
	v_mfma_f32_32x32x16_bf16 v[80:95], v[112:115], v[162:165], v[80:95]
	v_max3_f32 v211, v211, v74, v75
	s_waitcnt lgkmcnt(1)
	v_mfma_f32_32x32x16_bf16 v[80:95], v[116:119], v[166:169], v[80:95]
	v_max3_f32 v213, v213, v76, v77
	v_mfma_f32_32x32x16_bf16 v[80:95], v[120:123], v[170:173], v[80:95]
	v_max3_f32 v211, v211, v78, v79
	s_waitcnt lgkmcnt(0)
	v_mfma_f32_32x32x16_bf16 v[80:95], v[124:127], v[174:177], v[80:95]
	ds_read_b128 v[112:115], v219 offset:0
	ds_read_b128 v[116:119], v219 offset:4608
	ds_read_b128 v[120:123], v219 offset:9216
	s_cmp_eq_u32 s55, 0
	s_cselect_b32 s31, 0xff7fffff, 0
	s_nop 6
	v_max3_f32 v215, v80, v81, v82
	v_max3_f32 v209, v83, v84, v85
	v_max3_f32 v215, v215, v86, v87
	v_max3_f32 v209, v209, v88, v89
	v_max3_f32 v215, v215, v90, v91
	v_max3_f32 v209, v209, v92, v93
	v_max3_f32 v215, v215, v94, v95
	v_max3_f32 v209, v209, v211, v213
	v_max_f32_e32 v209, v209, v215
	v_cmp_lt_f32_e32 vcc, s58, v209
	s_cmp_eq_u32 s55, 0
	s_cbranch_scc1 .Latt_mla_rare
	s_cbranch_vccnz .Latt_mla_rare
